# index phase: batched key loads, fused relu canonicalize, kmax via LDS max-reduction + fewer global atomics (on top of DSA fast path/prefetch)
# speedup vs baseline: 1.0201x; 1.0053x over previous
; DI void phase_kmax(Frame& F) {
;     const bf16* H0 = (const bf16*)(F.ws + WS_BIG); unsigned* kmax = (unsigned*)(F.ws + WS_KMAX);
;     const int gw = F.bid * NWAVES + F.wave, NGW = F.G * NWAVES;
;     for (int r8 = gw; r8 < MTOK / 8; r8 += NGW) {
;         float best = 0.f;
.LBB0_196:
	s_cmp_lt_i32 s80, 3
	s_cselect_b64 s[0:1], -1, 0
	s_and_b64 s[14:15], s[0:1], s[6:7]
	s_andn2_b64 vcc, exec, s[14:15]
	s_cbranch_vccnz .LBB0_372
	v_lshlrev_b32_e32 v1, 2, v144
	v_add_u32_e32 v1, 0x23000, v1
	v_mov_b32_e32 v2, 0
	ds_write_b32 v1, v2
	s_waitcnt lgkmcnt(0)
	s_barrier
	s_lshl_b32 s0, s84, 3
	s_add_i32 s3, s0, s82
	s_cmpk_lt_i32 s3, 0x800
	v_and_b32_e32 v4, 3, v146
	s_cbranch_scc1 .LBB0_199
	v_and_b32_e32 v0, 3, v146
	s_cbranch_execz .LBB0_200
	s_branch .LBB0_205

; DI void phase_kmax(Frame& F) {
;     ...
;     for (int r8 = gw; r8 < MTOK / 8; r8 += NGW) {
;         float best = 0.f;
; #pragma unroll
;         for (int k = 0; k < 8; ++k) {
;             const bf16* p = H0 + (size_t)(r8 * 8 + k) * EVEN_LD + C_KB + 16 * F.lane;
;             const u32x4 a = *(const u32x4*)p, b = *(const u32x4*)(p + 8);
;             float ssq = 0.f;
; #pragma unroll
;             for (int q = 0; q < 4; ++q) { const float a0 = __uint_as_float(a[q] << 16), a1 = __uint_as_float(a[q] & 0xffff0000u), b0 = __uint_as_float(b[q] << 16), b1 = __uint_as_float(b[q] & 0xffff0000u);
;                 ssq += (a0 * a0 + a1 * a1) + (b0 * b0 + b1 * b1); }
;             ssq += __shfl_xor(ssq, 1); ssq += __shfl_xor(ssq, 2);
;             best = fmaxf(best, ssq);
.LBB0_202:
	s_add_i32 s6, s9, -7
	s_mul_hi_i32 s7, s6, 0x3600
	s_mul_i32 s6, s9, 0x3600
	s_add_i32 s12, s6, 0xfffe8600
	s_add_u32 s12, s22, s12
	s_addc_u32 s13, s23, s7
	s_waitcnt lgkmcnt(0)
	v_lshl_add_u64 v[12:13], s[12:13], 0, v[2:3]
	s_add_i32 s7, s9, -6
	s_add_i32 s12, s6, 0xfffebc00
	v_add_co_u32_e32 v8, vcc, 0xb802000, v12
	s_mul_hi_i32 s7, s7, 0x3600
	s_add_u32 s12, s22, s12
	v_addc_co_u32_e32 v9, vcc, 0, v13, vcc
	v_lshl_add_u64 v[12:13], v[12:13], 0, s[4:5]
	s_addc_u32 s13, s23, s7
	global_load_dwordx4 v[8:11], v[8:9], off
	v_lshl_add_u64 v[20:21], s[12:13], 0, v[2:3]
	global_load_dwordx4 v[12:15], v[12:13], off offset:16
	v_add_co_u32_e32 v16, vcc, s11, v20
	s_add_i32 s7, s9, -5
	s_nop 0
	v_addc_co_u32_e32 v17, vcc, 0, v21, vcc
	v_lshl_add_u64 v[20:21], v[20:21], 0, s[4:5]
	global_load_dwordx4 v[16:19], v[16:17], off
	s_add_i32 s12, s6, 0xfffef200
	global_load_dwordx4 v[20:23], v[20:21], off offset:16
	s_mul_hi_i32 s7, s7, 0x3600
	s_add_u32 s12, s22, s12
	s_addc_u32 s13, s23, s7
	v_lshl_add_u64 v[24:25], s[12:13], 0, v[2:3]
	v_lshl_add_u64 v[28:29], v[24:25], 0, s[4:5]
	v_add_co_u32_e32 v24, vcc, s11, v24
	s_add_i32 s7, s9, -4
	s_nop 0
	v_addc_co_u32_e32 v25, vcc, 0, v25, vcc
	global_load_dwordx4 v[24:27], v[24:25], off
	s_nop 0
	global_load_dwordx4 v[28:31], v[28:29], off offset:16
	s_add_i32 s12, s6, 0xffff2800
	s_mul_hi_i32 s7, s7, 0x3600
	s_add_u32 s12, s22, s12
	s_addc_u32 s13, s23, s7
	s_add_i32 s7, s9, -3
	s_mul_hi_i32 s7, s7, 0x3600
	s_waitcnt vmcnt(0)
	v_lshlrev_b32_e32 v7, 16, v8
	v_and_b32_e32 v8, 0xffff0000, v8
	v_lshlrev_b32_e32 v32, 16, v12
	v_and_b32_e32 v12, 0xffff0000, v12
	v_lshlrev_b32_e32 v33, 16, v9
	v_and_b32_e32 v9, 0xffff0000, v9
	v_lshlrev_b32_e32 v34, 16, v13
	v_and_b32_e32 v13, 0xffff0000, v13
	v_lshlrev_b32_e32 v35, 16, v10
	v_and_b32_e32 v10, 0xffff0000, v10
	v_lshlrev_b32_e32 v36, 16, v14
	v_and_b32_e32 v14, 0xffff0000, v14
	v_mul_f32_e32 v8, v8, v8
	v_mul_f32_e32 v12, v12, v12
	v_mul_f32_e32 v9, v9, v9
	v_mul_f32_e32 v13, v13, v13
	v_lshlrev_b32_e32 v37, 16, v11
	v_and_b32_e32 v11, 0xffff0000, v11
	v_lshlrev_b32_e32 v38, 16, v15
	v_and_b32_e32 v15, 0xffff0000, v15
	v_mul_f32_e32 v10, v10, v10
	v_mul_f32_e32 v14, v14, v14
	v_fmac_f32_e32 v8, v7, v7
	v_fmac_f32_e32 v12, v32, v32
	v_fmac_f32_e32 v9, v33, v33
	v_fmac_f32_e32 v13, v34, v34
	v_mul_f32_e32 v11, v11, v11
	v_mul_f32_e32 v15, v15, v15
	v_lshlrev_b32_e32 v39, 16, v16
	v_and_b32_e32 v16, 0xffff0000, v16
	v_lshlrev_b32_e32 v40, 16, v20
	v_and_b32_e32 v20, 0xffff0000, v20
	v_fmac_f32_e32 v10, v35, v35
	v_fmac_f32_e32 v14, v36, v36
	v_add_f32_e32 v8, v8, v12
	v_add_f32_e32 v9, v9, v13
	v_fmac_f32_e32 v11, v37, v37
	v_fmac_f32_e32 v15, v38, v38
	v_mul_f32_e32 v7, v16, v16
	v_mul_f32_e32 v16, v20, v20
	v_add_f32_e32 v10, v10, v14
	v_add_f32_e32 v8, v8, v9
	v_lshlrev_b32_e32 v41, 16, v17
	v_and_b32_e32 v17, 0xffff0000, v17
	v_lshlrev_b32_e32 v42, 16, v21
	v_and_b32_e32 v21, 0xffff0000, v21
	v_add_f32_e32 v11, v11, v15
	v_fmac_f32_e32 v7, v39, v39
	v_fmac_f32_e32 v16, v40, v40
	v_add_f32_e32 v8, v10, v8
	v_mul_f32_e32 v17, v17, v17
	v_add_f32_e32 v7, v7, v16
	v_add_f32_e32 v16, v11, v8
	v_mul_f32_e32 v8, v21, v21
	v_fmac_f32_e32 v17, v41, v41
	v_fmac_f32_e32 v8, v42, v42
	v_add_f32_e32 v8, v17, v8
	v_add_f32_e32 v7, v7, v8
	v_lshl_add_u64 v[8:9], s[12:13], 0, v[2:3]
	v_add_co_u32_e32 v10, vcc, s11, v8
	v_lshlrev_b32_e32 v17, 16, v18
	s_nop 0
	v_addc_co_u32_e32 v11, vcc, 0, v9, vcc
	global_load_dwordx4 v[12:15], v[10:11], off
	v_lshl_add_u64 v[8:9], v[8:9], 0, s[4:5]
	global_load_dwordx4 v[32:35], v[8:9], off offset:16
	v_and_b32_e32 v18, 0xffff0000, v18
	v_and_b32_e32 v8, 0xffff0000, v22
	v_lshlrev_b32_e32 v21, 16, v22
	v_mul_f32_e32 v9, v18, v18
	v_mul_f32_e32 v8, v8, v8
	v_fmac_f32_e32 v9, v17, v17
	v_fmac_f32_e32 v8, v21, v21
	ds_bpermute_b32 v20, v5, v16
	v_add_f32_e32 v8, v9, v8
	v_and_b32_e32 v9, 0xffff0000, v19
	v_add_f32_e32 v7, v8, v7
	v_lshlrev_b32_e32 v8, 16, v19
	v_and_b32_e32 v11, 0xffff0000, v23
	v_mul_f32_e32 v9, v9, v9
	v_lshlrev_b32_e32 v10, 16, v23
	v_fmac_f32_e32 v9, v8, v8
	v_mul_f32_e32 v8, v11, v11
	v_fmac_f32_e32 v8, v10, v10
	v_add_f32_e32 v8, v9, v8
	v_add_f32_e32 v9, v8, v7
	s_waitcnt lgkmcnt(0)
	v_add_f32_e32 v7, v16, v20
	v_and_b32_e32 v16, 0xffff0000, v24
	v_lshlrev_b32_e32 v11, 16, v24
	v_and_b32_e32 v18, 0xffff0000, v28
	v_mul_f32_e32 v16, v16, v16
	s_add_i32 s12, s6, 0xffff5e00
	v_lshlrev_b32_e32 v17, 16, v28
	v_fmac_f32_e32 v16, v11, v11
	v_mul_f32_e32 v11, v18, v18
	s_add_u32 s12, s22, s12
	v_fmac_f32_e32 v11, v17, v17
	v_and_b32_e32 v17, 0xffff0000, v25
	s_addc_u32 s13, s23, s7
	v_add_f32_e32 v11, v16, v11
	v_lshlrev_b32_e32 v16, 16, v25
	v_mul_f32_e32 v25, v17, v17
	v_lshl_add_u64 v[20:21], s[12:13], 0, v[2:3]
	v_fmac_f32_e32 v25, v16, v16
	v_add_co_u32_e32 v16, vcc, s11, v20
	v_and_b32_e32 v18, 0xffff0000, v29
	s_nop 0
	v_addc_co_u32_e32 v17, vcc, 0, v21, vcc
	v_mul_f32_e32 v28, v18, v18
	global_load_dwordx4 v[16:19], v[16:17], off
	v_lshl_add_u64 v[20:21], v[20:21], 0, s[4:5]
	global_load_dwordx4 v[20:23], v[20:21], off offset:16
	v_lshlrev_b32_e32 v24, 16, v29
	v_fmac_f32_e32 v28, v24, v24
	v_add_f32_e32 v24, v25, v28
	v_and_b32_e32 v25, 0xffff0000, v26
	v_add_f32_e32 v11, v11, v24
	v_lshlrev_b32_e32 v24, 16, v26
	v_and_b32_e32 v28, 0xffff0000, v30
	v_mul_f32_e32 v25, v25, v25
	v_lshlrev_b32_e32 v26, 16, v30
	v_fmac_f32_e32 v25, v24, v24
	v_mul_f32_e32 v24, v28, v28
	v_fmac_f32_e32 v24, v26, v26
	v_add_f32_e32 v24, v25, v24
	v_and_b32_e32 v25, 0xffff0000, v27
	v_add_f32_e32 v11, v24, v11
	v_lshlrev_b32_e32 v24, 16, v27
	v_and_b32_e32 v27, 0xffff0000, v31
	v_mul_f32_e32 v25, v25, v25
	v_lshlrev_b32_e32 v26, 16, v31
	v_fmac_f32_e32 v25, v24, v24
	v_mul_f32_e32 v24, v27, v27
	v_fmac_f32_e32 v24, v26, v26
	v_add_f32_e32 v24, v25, v24
	v_add_f32_e32 v11, v24, v11
	s_add_i32 s7, s9, -2
	s_add_i32 s12, s6, 0xffff9400
	s_mul_hi_i32 s7, s7, 0x3600
	s_add_u32 s12, s22, s12
	s_addc_u32 s13, s23, s7
	s_add_i32 s7, s9, -1
	s_waitcnt vmcnt(3)
; DI void phase_kmax(Frame& F) {
;     ...
;         for (int k = 0; k < 8; ++k) {
;             const bf16* p = H0 + (size_t)(r8 * 8 + k) * EVEN_LD + C_KB + 16 * F.lane;
;             const u32x4 a = *(const u32x4*)p, b = *(const u32x4*)(p + 8);
;             float ssq = 0.f;
; #pragma unroll
;             for (int q = 0; q < 4; ++q) { const float a0 = __uint_as_float(a[q] << 16), a1 = __uint_as_float(a[q] & 0xffff0000u), b0 = __uint_as_float(b[q] << 16), b1 = __uint_as_float(b[q] & 0xffff0000u);
;                 ssq += (a0 * a0 + a1 * a1) + (b0 * b0 + b1 * b1); }
;             ssq += __shfl_xor(ssq, 1); ssq += __shfl_xor(ssq, 2);
;             best = fmaxf(best, ssq);
	v_lshlrev_b32_e32 v24, 16, v12
	v_and_b32_e32 v12, 0xffff0000, v12
	s_waitcnt vmcnt(2)
	v_and_b32_e32 v26, 0xffff0000, v32
	v_mul_f32_e32 v12, v12, v12
	v_lshlrev_b32_e32 v25, 16, v32
	v_fmac_f32_e32 v12, v24, v24
	v_mul_f32_e32 v24, v26, v26
	v_fmac_f32_e32 v24, v25, v25
	v_add_f32_e32 v12, v12, v24
	v_lshlrev_b32_e32 v24, 16, v13
	v_and_b32_e32 v13, 0xffff0000, v13
	v_and_b32_e32 v26, 0xffff0000, v33
	v_mul_f32_e32 v13, v13, v13
	v_lshlrev_b32_e32 v25, 16, v33
	v_fmac_f32_e32 v13, v24, v24
	v_mul_f32_e32 v24, v26, v26
	v_fmac_f32_e32 v24, v25, v25
	v_add_f32_e32 v13, v13, v24
	v_add_f32_e32 v32, v12, v13
	v_lshl_add_u64 v[12:13], s[12:13], 0, v[2:3]
	v_add_co_u32_e32 v24, vcc, s11, v12
	v_lshlrev_b32_e32 v33, 16, v14
	s_nop 0
	v_addc_co_u32_e32 v25, vcc, 0, v13, vcc
	v_lshl_add_u64 v[12:13], v[12:13], 0, s[4:5]
	v_and_b32_e32 v14, 0xffff0000, v14
	global_load_dwordx4 v[28:31], v[12:13], off offset:16
	v_and_b32_e32 v12, 0xffff0000, v34
	v_lshlrev_b32_e32 v36, 16, v34
	v_mul_f32_e32 v13, v14, v14
	v_mul_f32_e32 v12, v12, v12
	v_fmac_f32_e32 v13, v33, v33
	v_fmac_f32_e32 v12, v36, v36
	v_add_f32_e32 v12, v13, v12
	v_and_b32_e32 v14, 0xffff0000, v15
	global_load_dwordx4 v[24:27], v[24:25], off
	v_add_f32_e32 v12, v12, v32
	v_lshlrev_b32_e32 v13, 16, v15
	v_and_b32_e32 v32, 0xffff0000, v35
	v_mul_f32_e32 v14, v14, v14
	v_lshlrev_b32_e32 v15, 16, v35
	v_fmac_f32_e32 v14, v13, v13
	v_mul_f32_e32 v13, v32, v32
	v_fmac_f32_e32 v13, v15, v15
	v_add_f32_e32 v13, v14, v13
	v_add_f32_e32 v41, v13, v12
	s_waitcnt vmcnt(3)
	v_and_b32_e32 v13, 0xffff0000, v16
	v_lshlrev_b32_e32 v12, 16, v16
	s_waitcnt vmcnt(2)
	v_and_b32_e32 v15, 0xffff0000, v20
	v_mul_f32_e32 v13, v13, v13
	v_lshlrev_b32_e32 v14, 16, v20
	v_fmac_f32_e32 v13, v12, v12
	v_mul_f32_e32 v12, v15, v15
	v_fmac_f32_e32 v12, v14, v14
	v_and_b32_e32 v14, 0xffff0000, v17
	v_add_f32_e32 v12, v13, v12
	v_lshlrev_b32_e32 v13, 16, v17
	v_and_b32_e32 v16, 0xffff0000, v21
	v_mul_f32_e32 v14, v14, v14
	v_lshlrev_b32_e32 v15, 16, v21
	v_fmac_f32_e32 v14, v13, v13
	v_mul_f32_e32 v13, v16, v16
	s_add_i32 s12, s6, 0xffffca00
	v_fmac_f32_e32 v13, v15, v15
	s_mul_hi_i32 s7, s7, 0x3600
	s_add_u32 s12, s22, s12
	v_add_f32_e32 v13, v14, v13
	s_addc_u32 s13, s23, s7
	v_add_f32_e32 v16, v12, v13
	v_lshl_add_u64 v[12:13], s[12:13], 0, v[2:3]
	v_add_co_u32_e32 v14, vcc, s11, v12
	v_lshlrev_b32_e32 v17, 16, v18
	s_nop 0
	v_addc_co_u32_e32 v15, vcc, 0, v13, vcc
	global_load_dwordx4 v[32:35], v[14:15], off
	v_lshl_add_u64 v[12:13], v[12:13], 0, s[4:5]
	global_load_dwordx4 v[36:39], v[12:13], off offset:16
	v_and_b32_e32 v12, 0xffff0000, v18
	v_and_b32_e32 v14, 0xffff0000, v22
	v_lshlrev_b32_e32 v13, 16, v22
	v_mul_f32_e32 v12, v12, v12
	v_mul_f32_e32 v14, v14, v14
	v_fmac_f32_e32 v12, v17, v17
	v_fmac_f32_e32 v14, v13, v13
	s_mul_hi_i32 s7, s9, 0x3600
	s_add_u32 s6, s22, s6
	ds_bpermute_b32 v40, v5, v11
	ds_bpermute_b32 v42, v5, v41
	v_add_f32_e32 v12, v12, v14
	v_and_b32_e32 v14, 0xffff0000, v19
	s_addc_u32 s7, s23, s7
	v_add_f32_e32 v12, v12, v16
	v_lshlrev_b32_e32 v13, 16, v19
	v_lshlrev_b32_e32 v15, 16, v23
	v_and_b32_e32 v16, 0xffff0000, v23
	v_mul_f32_e32 v14, v14, v14
	v_lshl_add_u64 v[22:23], s[6:7], 0, v[2:3]
	v_fmac_f32_e32 v14, v13, v13
	v_mul_f32_e32 v13, v16, v16
	v_add_co_u32_e32 v18, vcc, s11, v22
	v_fmac_f32_e32 v13, v15, v15
	s_nop 0
	v_addc_co_u32_e32 v19, vcc, 0, v23, vcc
	v_add_f32_e32 v13, v14, v13
	global_load_dwordx4 v[18:21], v[18:19], off
	v_lshl_add_u64 v[22:23], v[22:23], 0, s[4:5]
	v_add_f32_e32 v14, v13, v12
	s_waitcnt lgkmcnt(1)
	v_add_f32_e32 v11, v11, v40
	s_waitcnt lgkmcnt(0)
	v_add_f32_e32 v13, v41, v42
	global_load_dwordx4 v[40:43], v[22:23], off offset:16
	s_waitcnt vmcnt(5)
	v_and_b32_e32 v22, 0xffff0000, v28
	v_lshlrev_b32_e32 v44, 16, v28
	ds_bpermute_b32 v10, v5, v9
	s_waitcnt vmcnt(4)
; DI void phase_kmax(Frame& F) {
;     ...
; #pragma unroll
;         for (int k = 0; k < 8; ++k) {
;             const bf16* p = H0 + (size_t)(r8 * 8 + k) * EVEN_LD + C_KB + 16 * F.lane;
;             const u32x4 a = *(const u32x4*)p, b = *(const u32x4*)(p + 8);
;             float ssq = 0.f;
; #pragma unroll
;             for (int q = 0; q < 4; ++q) { const float a0 = __uint_as_float(a[q] << 16), a1 = __uint_as_float(a[q] & 0xffff0000u), b0 = __uint_as_float(b[q] << 16), b1 = __uint_as_float(b[q] & 0xffff0000u);
;                 ssq += (a0 * a0 + a1 * a1) + (b0 * b0 + b1 * b1); }
;             ssq += __shfl_xor(ssq, 1); ssq += __shfl_xor(ssq, 2);
;             best = fmaxf(best, ssq);
;         }
;         if ((F.lane & 3) == 0) atomicMax(kmax + ((r8 * 8) >> 12) * 16 + (F.lane >> 2), __float_as_uint(best));
	v_lshlrev_b32_e32 v17, 16, v24
	v_and_b32_e32 v24, 0xffff0000, v24
	v_mul_f32_e32 v23, v24, v24
	v_fmac_f32_e32 v23, v17, v17
	v_mul_f32_e32 v17, v22, v22
	v_fmac_f32_e32 v17, v44, v44
	v_add_f32_e32 v17, v23, v17
	v_and_b32_e32 v23, 0xffff0000, v25
	v_lshlrev_b32_e32 v22, 16, v25
	v_and_b32_e32 v25, 0xffff0000, v29
	v_mul_f32_e32 v23, v23, v23
	v_lshlrev_b32_e32 v24, 16, v29
	v_fmac_f32_e32 v23, v22, v22
	v_mul_f32_e32 v22, v25, v25
	v_fmac_f32_e32 v22, v24, v24
	v_add_f32_e32 v22, v23, v22
	v_and_b32_e32 v23, 0xffff0000, v26
	v_add_f32_e32 v17, v17, v22
	v_lshlrev_b32_e32 v22, 16, v26
	v_and_b32_e32 v25, 0xffff0000, v30
	v_mul_f32_e32 v23, v23, v23
	v_lshlrev_b32_e32 v24, 16, v30
	v_fmac_f32_e32 v23, v22, v22
	v_mul_f32_e32 v22, v25, v25
	v_fmac_f32_e32 v22, v24, v24
	v_add_f32_e32 v22, v23, v22
	v_and_b32_e32 v23, 0xffff0000, v27
	v_add_f32_e32 v17, v22, v17
	v_lshlrev_b32_e32 v22, 16, v27
	v_and_b32_e32 v25, 0xffff0000, v31
	v_mul_f32_e32 v23, v23, v23
	v_lshlrev_b32_e32 v24, 16, v31
	v_fmac_f32_e32 v23, v22, v22
	v_mul_f32_e32 v22, v25, v25
	v_fmac_f32_e32 v22, v24, v24
	v_add_f32_e32 v22, v23, v22
	v_add_f32_e32 v17, v22, v17
	ds_bpermute_b32 v16, v5, v14
	ds_bpermute_b32 v22, v5, v17
	s_waitcnt lgkmcnt(2)
	v_add_f32_e32 v9, v9, v10
	s_waitcnt vmcnt(3)
	v_and_b32_e32 v24, 0xffff0000, v32
	v_lshlrev_b32_e32 v23, 16, v32
	s_waitcnt vmcnt(2)
	v_and_b32_e32 v26, 0xffff0000, v36
	v_mul_f32_e32 v24, v24, v24
	v_lshlrev_b32_e32 v25, 16, v36
	v_fmac_f32_e32 v24, v23, v23
	v_mul_f32_e32 v23, v26, v26
	v_fmac_f32_e32 v23, v25, v25
	v_and_b32_e32 v25, 0xffff0000, v33
	v_add_f32_e32 v23, v24, v23
	v_lshlrev_b32_e32 v24, 16, v33
	v_and_b32_e32 v27, 0xffff0000, v37
	v_mul_f32_e32 v25, v25, v25
	v_lshlrev_b32_e32 v26, 16, v37
	v_fmac_f32_e32 v25, v24, v24
	v_mul_f32_e32 v24, v27, v27
	v_fmac_f32_e32 v24, v26, v26
	v_add_f32_e32 v24, v25, v24
	v_and_b32_e32 v25, 0xffff0000, v34
	v_add_f32_e32 v23, v23, v24
	v_lshlrev_b32_e32 v24, 16, v34
	v_and_b32_e32 v27, 0xffff0000, v38
	v_mul_f32_e32 v25, v25, v25
	v_lshlrev_b32_e32 v26, 16, v38
	v_fmac_f32_e32 v25, v24, v24
	v_mul_f32_e32 v24, v27, v27
	v_fmac_f32_e32 v24, v26, v26
	v_add_f32_e32 v24, v25, v24
	v_and_b32_e32 v25, 0xffff0000, v35
	v_add_f32_e32 v23, v24, v23
	v_lshlrev_b32_e32 v24, 16, v35
	v_and_b32_e32 v27, 0xffff0000, v39
	v_mul_f32_e32 v25, v25, v25
	v_lshlrev_b32_e32 v26, 16, v39
	v_fmac_f32_e32 v25, v24, v24
	v_mul_f32_e32 v24, v27, v27
	v_fmac_f32_e32 v24, v26, v26
	v_add_f32_e32 v24, v25, v24
	s_waitcnt vmcnt(1)
	v_lshlrev_b32_e32 v25, 16, v18
	v_and_b32_e32 v18, 0xffff0000, v18
	s_waitcnt vmcnt(0)
	v_and_b32_e32 v27, 0xffff0000, v40
	v_mul_f32_e32 v18, v18, v18
	v_lshlrev_b32_e32 v26, 16, v40
	v_fmac_f32_e32 v18, v25, v25
	v_mul_f32_e32 v25, v27, v27
	v_fmac_f32_e32 v25, v26, v26
	v_add_f32_e32 v18, v18, v25
	v_lshlrev_b32_e32 v25, 16, v19
	v_and_b32_e32 v19, 0xffff0000, v19
	v_and_b32_e32 v27, 0xffff0000, v41
	v_mul_f32_e32 v19, v19, v19
	v_lshlrev_b32_e32 v26, 16, v41
	v_fmac_f32_e32 v19, v25, v25
	v_mul_f32_e32 v25, v27, v27
	v_fmac_f32_e32 v25, v26, v26
	v_add_f32_e32 v19, v19, v25
	v_add_f32_e32 v18, v18, v19
	v_lshlrev_b32_e32 v19, 16, v20
	v_and_b32_e32 v20, 0xffff0000, v20
	v_and_b32_e32 v26, 0xffff0000, v42
	v_mul_f32_e32 v20, v20, v20
	v_lshlrev_b32_e32 v25, 16, v42
	v_fmac_f32_e32 v20, v19, v19
	v_mul_f32_e32 v19, v26, v26
	v_fmac_f32_e32 v19, v25, v25
	v_add_f32_e32 v19, v20, v19
	v_and_b32_e32 v20, 0xffff0000, v21
	v_add_f32_e32 v18, v19, v18
	v_lshlrev_b32_e32 v19, 16, v21
	v_and_b32_e32 v25, 0xffff0000, v43
	v_mul_f32_e32 v20, v20, v20
	v_lshlrev_b32_e32 v21, 16, v43
	v_fmac_f32_e32 v20, v19, v19
	v_mul_f32_e32 v19, v25, v25
	v_fmac_f32_e32 v19, v21, v21
	v_add_f32_e32 v19, v20, v19
	v_add_f32_e32 v23, v24, v23
	v_add_f32_e32 v21, v19, v18
	ds_bpermute_b32 v24, v5, v23
	ds_bpermute_b32 v25, v5, v21
	s_waitcnt lgkmcnt(3)
	v_add_f32_e32 v14, v14, v16
	s_waitcnt lgkmcnt(2)
	v_add_f32_e32 v17, v17, v22
	ds_bpermute_b32 v8, v6, v7
	s_waitcnt lgkmcnt(2)
	v_add_f32_e32 v18, v23, v24
	s_waitcnt lgkmcnt(1)
	v_add_f32_e32 v21, v21, v25
	ds_bpermute_b32 v10, v6, v9
	ds_bpermute_b32 v12, v6, v11
	ds_bpermute_b32 v15, v6, v13
	ds_bpermute_b32 v16, v6, v14
	ds_bpermute_b32 v19, v6, v17
	ds_bpermute_b32 v20, v6, v18
	ds_bpermute_b32 v22, v6, v21
	s_and_saveexec_b64 s[6:7], s[0:1]
	s_cbranch_execz .LBB0_201
	s_waitcnt lgkmcnt(7)
	v_add_f32_e32 v7, v7, v8
	s_waitcnt lgkmcnt(6)
	v_add_f32_e32 v8, v9, v10
	v_max3_f32 v7, v7, 0, v8
	s_waitcnt lgkmcnt(5)
	v_add_f32_e32 v8, v11, v12
	s_waitcnt lgkmcnt(4)
	v_add_f32_e32 v9, v13, v15
	s_ashr_i32 s12, s3, 5
	v_max3_f32 v7, v7, v8, v9
	s_waitcnt lgkmcnt(3)
	v_add_f32_e32 v8, v14, v16
	s_waitcnt lgkmcnt(2)
	v_add_f32_e32 v9, v17, v19
	s_and_b32 s12, s12, -16
	v_max3_f32 v7, v7, v8, v9
	s_waitcnt lgkmcnt(1)
	v_add_f32_e32 v8, v18, v20
	s_waitcnt lgkmcnt(0)
	v_add_f32_e32 v9, v21, v22
	s_ashr_i32 s13, s12, 31
	v_max3_f32 v7, v7, v8, v9
	s_lshl_b32 s13, s12, 2
	s_add_i32 s13, s13, 0x23000
	v_add_u32_e32 v8, s13, v144
	ds_max_u32 v8, v7
	s_branch .LBB0_201

; DI void phase_kmax(Frame& F) {
;     const bf16* H0 = (const bf16*)(F.ws + WS_BIG); unsigned* kmax = (unsigned*)(F.ws + WS_KMAX);
;     const int gw = F.bid * NWAVES + F.wave, NGW = F.G * NWAVES;
;     for (int r8 = gw; r8 < MTOK / 8; r8 += NGW) {
;         float best = 0.f;
; #pragma unroll
;         for (int k = 0; k < 8; ++k) {
;             const bf16* p = H0 + (size_t)(r8 * 8 + k) * EVEN_LD + C_KB + 16 * F.lane;
;             const u32x4 a = *(const u32x4*)p, b = *(const u32x4*)(p + 8);
;             float ssq = 0.f;
; #pragma unroll
;             for (int q = 0; q < 4; ++q) { const float a0 = __uint_as_float(a[q] << 16), a1 = __uint_as_float(a[q] & 0xffff0000u), b0 = __uint_as_float(b[q] << 16), b1 = __uint_as_float(b[q] & 0xffff0000u);
;                 ssq += (a0 * a0 + a1 * a1) + (b0 * b0 + b1 * b1); }
;             ssq += __shfl_xor(ssq, 1); ssq += __shfl_xor(ssq, 2);
;             best = fmaxf(best, ssq);
;         }
;         if ((F.lane & 3) == 0) atomicMax(kmax + ((r8 * 8) >> 12) * 16 + (F.lane >> 2), __float_as_uint(best));
;     }
; }
.LBB0_205:
	s_waitcnt lgkmcnt(0)
	s_barrier
	s_cmp_lg_u32 s82, 0
	s_cbranch_scc1 .Lkmax_done
	v_lshlrev_b32_e32 v2, 2, v144
	v_add_u32_e32 v5, 0x23000, v2
	ds_read_b32 v6, v5
	v_mov_b32_e32 v3, 0
	s_add_u32 s100, s22, 0x1c0000
	s_addc_u32 s101, s23, 0
	v_lshl_add_u64 v[2:3], s[100:101], 0, v[2:3]
	s_waitcnt lgkmcnt(0)
	v_cmp_ne_u32_e64 s[100:101], 0, v6
	s_nop 3
	s_and_saveexec_b64 s[98:99], s[100:101]
	global_atomic_umax v[2:3], v6, off
	s_or_b64 exec, exec, s[98:99]

; #define MFMA32(a, b, c) __builtin_amdgcn_mfma_f32_32x32x16_bf16((a), (b), (c), 0, 0, 0)
; DI void index_unit(Frame& F, int b, int t0) {
;     ...
;             for (int mt = 0; mt < 2; ++mt) {
;                 f32x16 x;
; #pragma unroll
;                 for (int i = 0; i < 16; ++i) x[i] = 0.f;
; #pragma unroll
;                 for (int st = 0; st < 4; ++st) x = MFMA32(qa[mt][st], kb[st], x);
;                 float s0v = 0.f, s1v = 0.f;
; #pragma unroll
;                 for (int i = 0; i < 8; ++i) { s0v += wv[mt][i] * fmaxf(x[i], 0.f); s1v += wv[mt][8 + i] * fmaxf(x[8 + i], 0.f); }
;                 const int tq0 = 4 * mt + 2 * hf;
;                 sc[tq0 * 4096 + s] = (s <= t0 + tq0) ? (s0v + 0.f) : -1e30f;
;                 sc[(tq0 + 1) * 4096 + s] = (s <= t0 + tq0 + 1) ? (s1v + 0.f) : -1e30f;
;             }
.LBB0_213:
	v_mfma_f32_32x32x16_bf16 v[0:15], v[16:19], v[60:63], 0
	v_cmp_le_i32_e32 vcc, v200, v195
	v_mfma_f32_32x32x16_bf16 v[0:15], v[20:23], v[56:59], v[0:15]
	v_mfma_f32_32x32x16_bf16 v[0:15], v[24:27], v[52:55], v[0:15]
	v_mfma_f32_32x32x16_bf16 v[0:15], v[28:31], v[48:51], v[0:15]
	s_nop 11
	v_max_f32_e32 v0, 0, v0
	v_fma_f32 v0, v89, v0, 0
	v_max_f32_e32 v1, 0, v1
	v_max_f32_e32 v8, 0, v8
	v_fmac_f32_e32 v0, v164, v1
	v_fma_f32 v8, v171, v8, 0
	v_max_f32_e32 v1, 0, v9
	v_fmac_f32_e32 v8, v172, v1
	v_max_f32_e32 v1, 0, v2
	v_fmac_f32_e32 v0, v165, v1
	v_max_f32_e32 v1, 0, v10
	v_fmac_f32_e32 v8, v173, v1
	v_max_f32_e32 v1, 0, v3
	v_fmac_f32_e32 v0, v166, v1
	v_max_f32_e32 v1, 0, v11
	v_fmac_f32_e32 v8, v174, v1
	v_max_f32_e32 v1, 0, v4
	v_fmac_f32_e32 v0, v167, v1
	v_max_f32_e32 v1, 0, v12
	v_fmac_f32_e32 v8, v175, v1
	v_max_f32_e32 v1, 0, v5
	v_fmac_f32_e32 v0, v168, v1
	v_max_f32_e32 v1, 0, v13
	v_fmac_f32_e32 v8, v176, v1
	v_max_f32_e32 v1, 0, v6
	v_fmac_f32_e32 v0, v169, v1
	v_max_f32_e32 v1, 0, v14
	v_fmac_f32_e32 v8, v177, v1
	v_max_f32_e32 v1, 0, v7
	v_fmac_f32_e32 v0, v170, v1
	v_max_f32_e32 v1, 0, v15
	v_add_f32_e32 v0, 0, v0
	v_fmac_f32_e32 v8, v178, v1
	v_cndmask_b32_e32 v0, v163, v0, vcc
	v_add_u32_e32 v1, 0xffff0000, v199
	ds_write_b32 v1, v0
	v_add_f32_e32 v0, 0, v8
	v_cmp_le_i32_e32 vcc, v200, v196
	v_add_u32_e32 v1, 0xffff4000, v199
	s_nop 0
	v_cndmask_b32_e32 v0, v163, v0, vcc
	ds_write_b32 v1, v0
	v_mfma_f32_32x32x16_bf16 v[0:15], v[32:35], v[60:63], 0
	v_cmp_le_i32_e32 vcc, v200, v197
	v_mfma_f32_32x32x16_bf16 v[0:15], v[36:39], v[56:59], v[0:15]
	v_mfma_f32_32x32x16_bf16 v[0:15], v[40:43], v[52:55], v[0:15]
	v_mfma_f32_32x32x16_bf16 v[0:15], v[44:47], v[48:51], v[0:15]
	s_nop 11
	v_max_f32_e32 v0, 0, v0
	v_fma_f32 v0, v179, v0, 0
	v_max_f32_e32 v1, 0, v1
	v_max_f32_e32 v8, 0, v8
	v_fmac_f32_e32 v0, v180, v1
	v_fma_f32 v8, v187, v8, 0
	v_max_f32_e32 v1, 0, v9
	v_fmac_f32_e32 v8, v188, v1
	v_max_f32_e32 v1, 0, v2
	v_fmac_f32_e32 v0, v181, v1
	v_max_f32_e32 v1, 0, v10
	v_fmac_f32_e32 v8, v189, v1
	v_max_f32_e32 v1, 0, v3
	v_fmac_f32_e32 v0, v182, v1
	v_max_f32_e32 v1, 0, v11
	v_fmac_f32_e32 v8, v190, v1
	v_max_f32_e32 v1, 0, v4
	v_fmac_f32_e32 v0, v183, v1
	v_max_f32_e32 v1, 0, v12
	v_fmac_f32_e32 v8, v191, v1
	v_max_f32_e32 v1, 0, v5
	v_fmac_f32_e32 v0, v184, v1
	v_max_f32_e32 v1, 0, v13
	v_fmac_f32_e32 v8, v192, v1
	v_max_f32_e32 v1, 0, v6
	v_fmac_f32_e32 v0, v185, v1
	v_max_f32_e32 v1, 0, v14
	v_fmac_f32_e32 v8, v193, v1
	v_max_f32_e32 v1, 0, v7
	v_fmac_f32_e32 v0, v186, v1
	v_max_f32_e32 v1, 0, v15
	v_fmac_f32_e32 v8, v194, v1
	v_add_f32_e32 v0, 0, v0
	v_cndmask_b32_e32 v0, v163, v0, vcc
	v_add_f32_e32 v1, 0, v8
	v_cmp_le_i32_e32 vcc, v200, v198
	v_add_u32_e32 v200, 0x100, v200
	s_nop 0
	v_cndmask_b32_e32 v1, v163, v1, vcc
	ds_write2st64_b32 v199, v0, v1 offset1:64
	v_add_u32_e32 v199, 0x400, v199
	s_waitcnt vmcnt(0)
	v_mov_b64_e32 v[60:61], v[68:69]
	v_mov_b64_e32 v[62:63], v[70:71]
	v_mov_b64_e32 v[56:57], v[64:65]
	v_mov_b64_e32 v[58:59], v[66:67]
	v_mov_b64_e32 v[52:53], v[72:73]
	v_mov_b64_e32 v[54:55], v[74:75]
	v_mov_b64_e32 v[48:49], v[76:77]
	v_mov_b64_e32 v[50:51], v[78:79]
	s_andn2_b64 vcc, exec, s[0:1]
	s_cbranch_vccz .LBB0_216

; DI unsigned f2ord(float f) { const unsigned u = __float_as_uint(f); return (u & 0x80000000u) ? ~u : (u | 0x80000000u); }
; DI void index_unit(Frame& F, int b, int t0) {
;     ...
;     const int t = t0 + w;
;     unsigned long long myword = 0ull;
;     for (int _r21 = 0; _r21 < (PROBE_PHASE == 21 ? 2 : 1); ++_r21)
;     if (t < 256) {
;         const int nbits = t + 1 - 64 * lane;
;         myword = nbits >= 64 ? ~0ull : (nbits <= 0 ? 0ull : ((1ull << nbits) - 1ull));
;     } else {
;         unsigned key[64];
; #pragma unroll
;         for (int i = 0; i < 64; ++i) { const int s = 64 * i + lane; key[i] = (s <= t) ? f2ord(sc[w * 4096 + s]) : 0u; }
.LBB0_216:
	s_add_i32 s34, s82, s4
	v_add_u32_e32 v0, s34, v93
	s_cmpk_lt_i32 s34, 0x100
	v_cmp_lt_i32_e64 s[0:1], 0, v0
	v_cmp_gt_i32_e32 vcc, 64, v0
	s_waitcnt lgkmcnt(0)
	s_barrier
	s_cbranch_scc1 .LBB0_206
	s_mov_b32 s98, 0x80000000
	ds_read2st64_b32 v[0:1], v94 offset1:1
	ds_read2st64_b32 v[4:5], v94 offset0:2 offset1:3
	ds_read_b32 v8, v94 offset:1024
	ds_read_b32 v6, v94 offset:1280
	ds_read_b32 v11, v94 offset:1536
	ds_read_b32 v7, v94 offset:1792
	ds_read_b32 v13, v94 offset:2048
	ds_read_b32 v9, v94 offset:2304
	ds_read_b32 v15, v94 offset:2560
	ds_read_b32 v10, v94 offset:2816
	ds_read_b32 v17, v94 offset:3072
	ds_read_b32 v12, v94 offset:3328
	ds_read_b32 v19, v94 offset:3584
	ds_read_b32 v14, v94 offset:3840
	s_waitcnt lgkmcnt(6)
	v_ashrrev_i32_e32 v2, 31, v8
	v_ashrrev_i32_e32 v3, 31, v6
	v_ashrrev_i32_e32 v66, 31, v11
	v_ashrrev_i32_e32 v67, 31, v7
	v_cmp_ge_i32_e64 s[0:1], s34, v95
	v_cmp_ge_i32_e64 s[4:5], s34, v96
	v_cmp_ge_i32_e64 s[6:7], s34, v97
	v_cmp_ge_i32_e64 s[8:9], s34, v98
	v_bitop3_b32 v8, v8, v2, s98 bitop3:0x1e
	v_bitop3_b32 v6, v6, v3, s98 bitop3:0x1e
	v_bitop3_b32 v11, v11, v66, s98 bitop3:0x1e
	v_bitop3_b32 v7, v7, v67, s98 bitop3:0x1e
	v_cndmask_b32_e64 v8, 0, v8, s[0:1]
	v_cndmask_b32_e64 v6, 0, v6, s[4:5]
	v_cndmask_b32_e64 v11, 0, v11, s[6:7]
	v_cndmask_b32_e64 v7, 0, v7, s[8:9]
	v_ashrrev_i32_e32 v2, 31, v13
	v_ashrrev_i32_e32 v3, 31, v9
	v_cmp_ge_i32_e64 s[0:1], s34, v99
	v_cmp_ge_i32_e64 s[4:5], s34, v100
	v_bitop3_b32 v13, v13, v2, s98 bitop3:0x1e
	v_bitop3_b32 v9, v9, v3, s98 bitop3:0x1e
	v_cndmask_b32_e64 v13, 0, v13, s[0:1]
	v_cndmask_b32_e64 v9, 0, v9, s[4:5]
	ds_read_b32 v21, v94 offset:4096
	ds_read_b32 v16, v94 offset:4352
	ds_read_b32 v23, v94 offset:4608
	ds_read_b32 v18, v94 offset:4864
	ds_read_b32 v25, v94 offset:5120
	ds_read_b32 v20, v94 offset:5376
	s_waitcnt lgkmcnt(6)
	v_ashrrev_i32_e32 v2, 31, v15
	v_ashrrev_i32_e32 v3, 31, v10
	v_ashrrev_i32_e32 v66, 31, v17
	v_ashrrev_i32_e32 v67, 31, v12
	v_cmp_ge_i32_e64 s[0:1], s34, v101
	v_cmp_ge_i32_e64 s[4:5], s34, v102
	v_cmp_ge_i32_e64 s[6:7], s34, v103
	v_cmp_ge_i32_e64 s[8:9], s34, v104
	v_bitop3_b32 v15, v15, v2, s98 bitop3:0x1e
	v_bitop3_b32 v10, v10, v3, s98 bitop3:0x1e
	v_bitop3_b32 v17, v17, v66, s98 bitop3:0x1e
	v_bitop3_b32 v12, v12, v67, s98 bitop3:0x1e
	v_cndmask_b32_e64 v15, 0, v15, s[0:1]
	v_cndmask_b32_e64 v10, 0, v10, s[4:5]
	v_cndmask_b32_e64 v17, 0, v17, s[6:7]
	v_cndmask_b32_e64 v12, 0, v12, s[8:9]
	v_ashrrev_i32_e32 v2, 31, v19
	v_ashrrev_i32_e32 v3, 31, v14
	v_cmp_ge_i32_e64 s[0:1], s34, v105
	v_cmp_ge_i32_e64 s[4:5], s34, v106
	v_bitop3_b32 v19, v19, v2, s98 bitop3:0x1e
	v_bitop3_b32 v14, v14, v3, s98 bitop3:0x1e
	v_cndmask_b32_e64 v19, 0, v19, s[0:1]
	v_cndmask_b32_e64 v14, 0, v14, s[4:5]
	ds_read_b32 v27, v94 offset:5632
	ds_read_b32 v22, v94 offset:5888
	ds_read_b32 v29, v94 offset:6144
	ds_read_b32 v24, v94 offset:6400
	ds_read_b32 v31, v94 offset:6656
	ds_read_b32 v26, v94 offset:6912
	s_waitcnt lgkmcnt(6)
	v_ashrrev_i32_e32 v2, 31, v21
	v_ashrrev_i32_e32 v3, 31, v16
	v_ashrrev_i32_e32 v66, 31, v23
	v_ashrrev_i32_e32 v67, 31, v18
	v_cmp_ge_i32_e64 s[0:1], s34, v108
	v_cmp_ge_i32_e64 s[4:5], s34, v109
	v_cmp_ge_i32_e64 s[6:7], s34, v110
	v_cmp_ge_i32_e64 s[8:9], s34, v111
	v_bitop3_b32 v21, v21, v2, s98 bitop3:0x1e
	v_bitop3_b32 v16, v16, v3, s98 bitop3:0x1e
	v_bitop3_b32 v23, v23, v66, s98 bitop3:0x1e
	v_bitop3_b32 v18, v18, v67, s98 bitop3:0x1e
	v_cndmask_b32_e64 v21, 0, v21, s[0:1]
	v_cndmask_b32_e64 v16, 0, v16, s[4:5]
	v_cndmask_b32_e64 v23, 0, v23, s[6:7]
	v_cndmask_b32_e64 v18, 0, v18, s[8:9]
	v_ashrrev_i32_e32 v2, 31, v25
	v_ashrrev_i32_e32 v3, 31, v20
	v_cmp_ge_i32_e64 s[0:1], s34, v112
	v_cmp_ge_i32_e64 s[4:5], s34, v113
	v_bitop3_b32 v25, v25, v2, s98 bitop3:0x1e
	v_bitop3_b32 v20, v20, v3, s98 bitop3:0x1e
	v_cndmask_b32_e64 v25, 0, v25, s[0:1]
	v_cndmask_b32_e64 v20, 0, v20, s[4:5]
	ds_read_b32 v33, v94 offset:7168
	ds_read_b32 v28, v94 offset:7424
	ds_read_b32 v35, v94 offset:7680
	ds_read_b32 v30, v94 offset:7936
	ds_read_b32 v37, v94 offset:8192
	ds_read_b32 v32, v94 offset:8448
	s_waitcnt lgkmcnt(6)
	v_ashrrev_i32_e32 v2, 31, v27
	v_ashrrev_i32_e32 v3, 31, v22
	v_ashrrev_i32_e32 v66, 31, v29
	v_ashrrev_i32_e32 v67, 31, v24
	v_cmp_ge_i32_e64 s[0:1], s34, v114
	v_cmp_ge_i32_e64 s[4:5], s34, v115
	v_cmp_ge_i32_e64 s[6:7], s34, v116
	v_cmp_ge_i32_e64 s[8:9], s34, v117
	v_bitop3_b32 v27, v27, v2, s98 bitop3:0x1e
	v_bitop3_b32 v22, v22, v3, s98 bitop3:0x1e
	v_bitop3_b32 v29, v29, v66, s98 bitop3:0x1e
	v_bitop3_b32 v24, v24, v67, s98 bitop3:0x1e
	v_cndmask_b32_e64 v27, 0, v27, s[0:1]
	v_cndmask_b32_e64 v22, 0, v22, s[4:5]
	v_cndmask_b32_e64 v29, 0, v29, s[6:7]
	v_cndmask_b32_e64 v24, 0, v24, s[8:9]
	v_ashrrev_i32_e32 v2, 31, v31
	v_ashrrev_i32_e32 v3, 31, v26
	v_cmp_ge_i32_e64 s[0:1], s34, v118
	v_cmp_ge_i32_e64 s[4:5], s34, v119
	v_bitop3_b32 v31, v31, v2, s98 bitop3:0x1e
	v_bitop3_b32 v26, v26, v3, s98 bitop3:0x1e
	v_cndmask_b32_e64 v31, 0, v31, s[0:1]
	v_cndmask_b32_e64 v26, 0, v26, s[4:5]
	ds_read_b32 v39, v94 offset:8704
	ds_read_b32 v34, v94 offset:8960
	ds_read_b32 v41, v94 offset:9216
	ds_read_b32 v36, v94 offset:9472
	ds_read_b32 v43, v94 offset:9728
	ds_read_b32 v38, v94 offset:9984
	s_waitcnt lgkmcnt(6)
; DI unsigned f2ord(float f) { const unsigned u = __float_as_uint(f); return (u & 0x80000000u) ? ~u : (u | 0x80000000u); }
; DI void index_unit(Frame& F, int b, int t0) {
;     ...
;     if (t < 256) {
;         const int nbits = t + 1 - 64 * lane;
;         myword = nbits >= 64 ? ~0ull : (nbits <= 0 ? 0ull : ((1ull << nbits) - 1ull));
;     } else {
;         unsigned key[64];
; #pragma unroll
;         for (int i = 0; i < 64; ++i) { const int s = 64 * i + lane; key[i] = (s <= t) ? f2ord(sc[w * 4096 + s]) : 0u; }
	v_ashrrev_i32_e32 v2, 31, v33
	v_ashrrev_i32_e32 v3, 31, v28
	v_ashrrev_i32_e32 v66, 31, v35
	v_ashrrev_i32_e32 v67, 31, v30
	v_cmp_ge_i32_e64 s[0:1], s34, v120
	v_cmp_ge_i32_e64 s[4:5], s34, v121
	v_cmp_ge_i32_e64 s[6:7], s34, v122
	v_cmp_ge_i32_e64 s[8:9], s34, v123
	v_bitop3_b32 v33, v33, v2, s98 bitop3:0x1e
	v_bitop3_b32 v28, v28, v3, s98 bitop3:0x1e
	v_bitop3_b32 v35, v35, v66, s98 bitop3:0x1e
	v_bitop3_b32 v30, v30, v67, s98 bitop3:0x1e
	v_cndmask_b32_e64 v33, 0, v33, s[0:1]
	v_cndmask_b32_e64 v28, 0, v28, s[4:5]
	v_cndmask_b32_e64 v35, 0, v35, s[6:7]
	v_cndmask_b32_e64 v30, 0, v30, s[8:9]
	v_ashrrev_i32_e32 v2, 31, v37
	v_ashrrev_i32_e32 v3, 31, v32
	v_cmp_ge_i32_e64 s[0:1], s34, v125
	v_cmp_ge_i32_e64 s[4:5], s34, v126
	v_bitop3_b32 v37, v37, v2, s98 bitop3:0x1e
	v_bitop3_b32 v32, v32, v3, s98 bitop3:0x1e
	v_cndmask_b32_e64 v37, 0, v37, s[0:1]
	v_cndmask_b32_e64 v32, 0, v32, s[4:5]
	ds_read_b32 v45, v94 offset:10240
	ds_read_b32 v40, v94 offset:10496
	ds_read_b32 v47, v94 offset:10752
	ds_read_b32 v42, v94 offset:11008
	ds_read_b32 v49, v94 offset:11264
	ds_read_b32 v44, v94 offset:11520
	s_waitcnt lgkmcnt(6)
	v_ashrrev_i32_e32 v2, 31, v39
	v_ashrrev_i32_e32 v3, 31, v34
	v_ashrrev_i32_e32 v66, 31, v41
	v_ashrrev_i32_e32 v67, 31, v36
	v_cmp_ge_i32_e64 s[0:1], s34, v127
	v_cmp_ge_i32_e64 s[4:5], s34, v128
	v_cmp_ge_i32_e64 s[6:7], s34, v129
	v_cmp_ge_i32_e64 s[8:9], s34, v130
	v_bitop3_b32 v39, v39, v2, s98 bitop3:0x1e
	v_bitop3_b32 v34, v34, v3, s98 bitop3:0x1e
	v_bitop3_b32 v41, v41, v66, s98 bitop3:0x1e
	v_bitop3_b32 v36, v36, v67, s98 bitop3:0x1e
	v_cndmask_b32_e64 v39, 0, v39, s[0:1]
	v_cndmask_b32_e64 v34, 0, v34, s[4:5]
	v_cndmask_b32_e64 v41, 0, v41, s[6:7]
	v_cndmask_b32_e64 v36, 0, v36, s[8:9]
	v_ashrrev_i32_e32 v2, 31, v43
	v_ashrrev_i32_e32 v3, 31, v38
	v_cmp_ge_i32_e64 s[0:1], s34, v131
	v_cmp_ge_i32_e64 s[4:5], s34, v132
	v_bitop3_b32 v43, v43, v2, s98 bitop3:0x1e
	v_bitop3_b32 v38, v38, v3, s98 bitop3:0x1e
	v_cndmask_b32_e64 v43, 0, v43, s[0:1]
	v_cndmask_b32_e64 v38, 0, v38, s[4:5]
	ds_read_b32 v51, v94 offset:11776
	ds_read_b32 v46, v94 offset:12032
	ds_read_b32 v53, v94 offset:12288
	ds_read_b32 v48, v94 offset:12544
	ds_read_b32 v55, v94 offset:12800
	ds_read_b32 v50, v94 offset:13056
	s_waitcnt lgkmcnt(6)
	v_ashrrev_i32_e32 v2, 31, v45
	v_ashrrev_i32_e32 v3, 31, v40
	v_ashrrev_i32_e32 v66, 31, v47
	v_ashrrev_i32_e32 v67, 31, v42
	v_cmp_ge_i32_e64 s[0:1], s34, v133
	v_cmp_ge_i32_e64 s[4:5], s34, v134
	v_cmp_ge_i32_e64 s[6:7], s34, v135
	v_cmp_ge_i32_e64 s[8:9], s34, v136
	v_bitop3_b32 v45, v45, v2, s98 bitop3:0x1e
	v_bitop3_b32 v40, v40, v3, s98 bitop3:0x1e
	v_bitop3_b32 v47, v47, v66, s98 bitop3:0x1e
	v_bitop3_b32 v42, v42, v67, s98 bitop3:0x1e
	v_cndmask_b32_e64 v45, 0, v45, s[0:1]
	v_cndmask_b32_e64 v40, 0, v40, s[4:5]
	v_cndmask_b32_e64 v47, 0, v47, s[6:7]
	v_cndmask_b32_e64 v42, 0, v42, s[8:9]
	v_ashrrev_i32_e32 v2, 31, v49
	v_ashrrev_i32_e32 v3, 31, v44
	v_cmp_ge_i32_e64 s[0:1], s34, v137
	v_cmp_ge_i32_e64 s[4:5], s34, v138
	v_bitop3_b32 v49, v49, v2, s98 bitop3:0x1e
	v_bitop3_b32 v44, v44, v3, s98 bitop3:0x1e
	v_cndmask_b32_e64 v49, 0, v49, s[0:1]
	v_cndmask_b32_e64 v44, 0, v44, s[4:5]
	ds_read_b32 v57, v94 offset:13312
	ds_read_b32 v52, v94 offset:13568
	ds_read_b32 v59, v94 offset:13824
	ds_read_b32 v54, v94 offset:14080
	ds_read_b32 v61, v94 offset:14336
	ds_read_b32 v56, v94 offset:14592
	s_waitcnt lgkmcnt(6)
	v_ashrrev_i32_e32 v2, 31, v51
	v_ashrrev_i32_e32 v3, 31, v46
	v_ashrrev_i32_e32 v66, 31, v53
	v_ashrrev_i32_e32 v67, 31, v48
	v_cmp_ge_i32_e64 s[0:1], s34, v139
	v_cmp_ge_i32_e64 s[4:5], s34, v140
	v_cmp_ge_i32_e64 s[6:7], s34, v142
	v_cmp_ge_i32_e64 s[8:9], s34, v143
	v_bitop3_b32 v51, v51, v2, s98 bitop3:0x1e
	v_bitop3_b32 v46, v46, v3, s98 bitop3:0x1e
	v_bitop3_b32 v53, v53, v66, s98 bitop3:0x1e
	v_bitop3_b32 v48, v48, v67, s98 bitop3:0x1e
	v_cndmask_b32_e64 v51, 0, v51, s[0:1]
	v_cndmask_b32_e64 v46, 0, v46, s[4:5]
	v_cndmask_b32_e64 v53, 0, v53, s[6:7]
	v_cndmask_b32_e64 v48, 0, v48, s[8:9]
	v_ashrrev_i32_e32 v2, 31, v55
	v_ashrrev_i32_e32 v3, 31, v50
	v_cmp_ge_i32_e64 s[0:1], s34, v145
	v_cmp_ge_i32_e64 s[4:5], s34, v147
	v_bitop3_b32 v55, v55, v2, s98 bitop3:0x1e
	v_bitop3_b32 v50, v50, v3, s98 bitop3:0x1e
	v_cndmask_b32_e64 v55, 0, v55, s[0:1]
	v_cndmask_b32_e64 v50, 0, v50, s[4:5]
	ds_read_b32 v63, v94 offset:14848
	ds_read_b32 v58, v94 offset:15104
	ds_read_b32 v64, v94 offset:15360
	ds_read_b32 v60, v94 offset:15616
	ds_read_b32 v65, v94 offset:15872
	ds_read_b32 v62, v94 offset:16128
	s_waitcnt lgkmcnt(6)
	v_ashrrev_i32_e32 v2, 31, v57
	v_ashrrev_i32_e32 v3, 31, v52
	v_ashrrev_i32_e32 v66, 31, v59
	v_ashrrev_i32_e32 v67, 31, v54
	v_cmp_ge_i32_e64 s[0:1], s34, v148
	v_cmp_ge_i32_e64 s[4:5], s34, v149
	v_cmp_ge_i32_e64 s[6:7], s34, v150
	v_cmp_ge_i32_e64 s[8:9], s34, v151
	v_bitop3_b32 v57, v57, v2, s98 bitop3:0x1e
	v_bitop3_b32 v52, v52, v3, s98 bitop3:0x1e
	v_bitop3_b32 v59, v59, v66, s98 bitop3:0x1e
	v_bitop3_b32 v54, v54, v67, s98 bitop3:0x1e
	v_cndmask_b32_e64 v57, 0, v57, s[0:1]
	v_cndmask_b32_e64 v52, 0, v52, s[4:5]
	v_cndmask_b32_e64 v59, 0, v59, s[6:7]
	v_cndmask_b32_e64 v54, 0, v54, s[8:9]
	v_ashrrev_i32_e32 v2, 31, v61
	v_ashrrev_i32_e32 v3, 31, v56
	v_cmp_ge_i32_e64 s[0:1], s34, v152
	v_cmp_ge_i32_e64 s[4:5], s34, v153
	v_bitop3_b32 v61, v61, v2, s98 bitop3:0x1e
	v_bitop3_b32 v56, v56, v3, s98 bitop3:0x1e
	v_cndmask_b32_e64 v61, 0, v61, s[0:1]
	v_cndmask_b32_e64 v56, 0, v56, s[4:5]
	s_waitcnt lgkmcnt(0)
	v_ashrrev_i32_e32 v2, 31, v63
	v_ashrrev_i32_e32 v3, 31, v58
	v_ashrrev_i32_e32 v66, 31, v64
	v_ashrrev_i32_e32 v67, 31, v60
	v_cmp_ge_i32_e64 s[0:1], s34, v154
	v_cmp_ge_i32_e64 s[4:5], s34, v155
	v_cmp_ge_i32_e64 s[6:7], s34, v156
	v_cmp_ge_i32_e64 s[8:9], s34, v157
	v_bitop3_b32 v63, v63, v2, s98 bitop3:0x1e
	v_bitop3_b32 v58, v58, v3, s98 bitop3:0x1e
	v_bitop3_b32 v64, v64, v66, s98 bitop3:0x1e
	v_bitop3_b32 v60, v60, v67, s98 bitop3:0x1e
	v_cndmask_b32_e64 v63, 0, v63, s[0:1]
	v_cndmask_b32_e64 v58, 0, v58, s[4:5]
	v_cndmask_b32_e64 v64, 0, v64, s[6:7]
	v_cndmask_b32_e64 v60, 0, v60, s[8:9]
	v_ashrrev_i32_e32 v2, 31, v65
	v_ashrrev_i32_e32 v3, 31, v62
	v_cmp_ge_i32_e64 s[0:1], s34, v158
	v_cmp_ge_i32_e64 s[4:5], s34, v159
	v_bitop3_b32 v65, v65, v2, s98 bitop3:0x1e
	v_bitop3_b32 v62, v62, v3, s98 bitop3:0x1e
	v_cndmask_b32_e64 v65, 0, v65, s[0:1]
	v_cndmask_b32_e64 v62, 0, v62, s[4:5]
